# NA task prologue no longer waits for all five prefetched rows before its set-up; diff-attention first tile barrier moved to the first fragment read with a counted wait
# speedup vs baseline: 1.0088x; 1.0034x over previous
.LBB0_233:
	s_cmp_lt_i32 s7, -11
	s_mov_b32 s78, 0
	s_cbranch_scc1 .LBB0_229
	s_waitcnt lgkmcnt(0)
	v_pk_add_f32 v[0:1], v[0:1], v[2:3]
	v_readlane_b32 s7, v252, 9
	v_mul_f32_e32 v0, v0, v1
	v_mul_f32_e32 v1, 0x4f800000, v0
	v_cmp_gt_f32_e32 vcc, s79, v0
	s_max_u32 s6, s6, 4
	s_min_u32 s7, s9, 56
	v_cndmask_b32_e32 v0, v0, v1, vcc
	v_sqrt_f32_e32 v1, v0
	s_mul_i32 s9, s6, 0x7c
	v_add_u32_e32 v4, s9, v162
	s_mulk_i32 s3, 0x1f0
	v_add_u32_e32 v2, -1, v1
	v_fma_f32 v3, -v2, v1, v0
	v_cmp_ge_f32_e64 s[74:75], 0, v3
	v_add_u32_e32 v3, 1, v1
	v_subrev_u32_e32 v147, s3, v4
	v_cndmask_b32_e64 v2, v1, v2, s[74:75]
	v_fma_f32 v1, -v3, v1, v0
	v_cmp_lt_f32_e64 s[74:75], 0, v1
	s_max_i32 s3, s8, 4
	v_readlane_b32 s8, v255, 34
	v_cndmask_b32_e64 v1, v2, v3, s[74:75]
	v_mul_f32_e32 v2, 0x37800000, v1
	v_cndmask_b32_e32 v1, v1, v2, vcc
	v_cmp_class_f32_e32 vcc, v0, v215
	v_readlane_b32 s9, v255, 35
	v_mov_b32_e32 v16, 0
	v_cndmask_b32_e32 v0, v1, v0, vcc
	v_fmamk_f32 v0, v0, 0x3f8147ae, v139
	v_add_f32_e32 v0, 0x3a83126f, v0
	v_cndmask_b32_e64 v32, v233, -v0, s[8:9]
	v_readlane_b32 s8, v255, 36
	v_readlane_b32 s9, v255, 37
	s_add_i32 s3, s3, -4
	v_mov_b32_e32 v17, v16
	v_cndmask_b32_e64 v48, v233, -v0, s[8:9]
	v_readlane_b32 s8, v255, 38
	v_readlane_b32 s9, v255, 39
	s_min_u32 s81, s3, 56
	v_cndmask_b32_e64 v49, v233, -v0, s[14:15]
	v_cndmask_b32_e64 v33, v233, -v0, s[8:9]
	v_cndmask_b32_e64 v34, v233, -v0, s[16:17]
	v_cndmask_b32_e64 v50, v233, -v0, s[18:19]
	v_cndmask_b32_e64 v35, v233, -v0, s[20:21]
	v_cndmask_b32_e64 v51, v233, -v0, s[22:23]
	v_cndmask_b32_e64 v36, v233, -v0, s[24:25]
	v_cndmask_b32_e64 v52, v233, -v0, s[26:27]
	v_cndmask_b32_e64 v37, v233, -v0, s[28:29]
	v_cndmask_b32_e64 v53, v233, -v0, s[30:31]
	v_cndmask_b32_e64 v38, v233, -v0, s[34:35]
	v_cndmask_b32_e64 v54, v233, -v0, s[36:37]
	v_cndmask_b32_e64 v39, v233, -v0, s[38:39]
	v_cndmask_b32_e64 v55, v233, -v0, s[40:41]
	v_cndmask_b32_e64 v40, v233, -v0, s[42:43]
	v_cndmask_b32_e64 v56, v233, -v0, s[44:45]
	v_cndmask_b32_e64 v41, v233, -v0, s[46:47]
	v_cndmask_b32_e64 v57, v233, -v0, s[48:49]
	v_cndmask_b32_e64 v42, v233, -v0, s[50:51]
	v_cndmask_b32_e64 v58, v233, -v0, s[52:53]
	v_cndmask_b32_e64 v43, v233, -v0, s[54:55]
	v_cndmask_b32_e64 v59, v233, -v0, s[56:57]
	v_cndmask_b32_e64 v44, v233, -v0, s[58:59]
	v_cndmask_b32_e64 v60, v233, -v0, s[60:61]
	v_cndmask_b32_e64 v45, v233, -v0, s[62:63]
	v_cndmask_b32_e64 v61, v233, -v0, s[64:65]
	v_cndmask_b32_e64 v46, v233, -v0, s[66:67]
	v_cndmask_b32_e64 v62, v233, -v0, s[68:69]
	v_cndmask_b32_e64 v47, v233, -v0, s[70:71]
	v_cndmask_b32_e64 v63, v233, -v0, s[72:73]
	v_mov_b32_e32 v18, v16
	v_mov_b32_e32 v19, v16
	v_mov_b32_e32 v20, v16
	v_mov_b32_e32 v21, v16
	v_mov_b32_e32 v22, v16
	v_mov_b32_e32 v23, v16
	v_mov_b32_e32 v24, v16
	v_mov_b32_e32 v25, v16
	v_mov_b32_e32 v26, v16
	v_mov_b32_e32 v27, v16
	v_mov_b32_e32 v28, v16
	v_mov_b32_e32 v29, v16
	v_mov_b32_e32 v30, v16
	v_mov_b32_e32 v31, v16
	v_mov_b64_e32 v[0:1], v[16:17]
	s_mov_b32 s12, s87
	s_sub_i32 s7, s7, s6
	s_add_i32 s3, s81, 7
	s_mov_b32 s87, -12
	s_mov_b32 s8, 5
	v_readlane_b32 s9, v252, 50
	v_mov_b64_e32 v[2:3], v[18:19]
	v_mov_b64_e32 v[4:5], v[20:21]
	v_mov_b64_e32 v[6:7], v[22:23]
	v_mov_b64_e32 v[8:9], v[24:25]
	v_mov_b64_e32 v[10:11], v[26:27]
	v_mov_b64_e32 v[12:13], v[28:29]
	v_mov_b64_e32 v[14:15], v[30:31]
	v_mov_b32_e32 v64, v16
	s_mov_b32 s10, 0
